# od_win epilogue 8-lane sum-of-squares butterflies via DPP operand permutes instead of ds_bpermute round trips
# baseline (speedup 1.0000x reference)
.LBB0_263:
	s_cmp_lt_u32 s8, 8
	s_cselect_b64 vcc, -1, 0
	s_and_b64 s[6:7], vcc, exec
	s_mov_b32 s6, 0x373c000
	v_readlane_b32 s12, v253, 12
	s_cselect_b32 s6, s6, 0x5b3c000
	v_readlane_b32 s18, v253, 18
	v_readlane_b32 s19, v253, 19
	v_readlane_b32 s20, v253, 20
	v_readlane_b32 s21, v253, 21
	s_cselect_b32 s8, s18, s20
	s_cselect_b32 s11, s19, s21
	s_add_u32 s6, s48, s6
	s_addc_u32 s7, s49, 0
	v_lshlrev_b32_e32 v66, 3, v111
	s_add_u32 s10, s8, s0
	v_and_b32_e32 v83, 56, v66
	s_addc_u32 s11, s11, s1
	v_lshlrev_b32_e32 v66, 2, v83
	global_load_dwordx4 v[70:73], v66, s[10:11]
	s_nop 0
	global_load_dwordx4 v[66:69], v66, s[10:11] offset:16
	v_and_b32_e32 v75, 64, v200
	v_xor_b32_e32 v74, 1, v200
	v_add_u32_e32 v95, 64, v75
	v_cndmask_b32_e32 v80, 1.0, v197, vcc
	v_cmp_lt_i32_e32 vcc, v74, v95
	v_pk_mul_f32 v[76:77], v[58:59], v[58:59]
	v_pk_mul_f32 v[88:89], v[50:51], v[50:51]
	v_cndmask_b32_e32 v74, v200, v74, vcc
	v_lshlrev_b32_e32 v82, 2, v74
	v_xor_b32_e32 v74, 2, v200
	v_cmp_lt_i32_e32 vcc, v74, v95
	v_pk_mul_f32 v[86:87], v[52:53], v[52:53]
	v_mov_b32_e32 v90, v88
	v_cndmask_b32_e32 v74, v200, v74, vcc
	v_lshlrev_b32_e32 v81, 2, v74
	v_pk_mul_f32 v[74:75], v[60:61], v[60:61]
	v_mov_b32_e32 v91, v76
	v_mov_b32_e32 v76, v89
	v_pk_add_f32 v[76:77], v[90:91], v[76:77]
	v_mov_b32_e32 v92, v86
	v_mov_b32_e32 v93, v74
	v_pk_mul_f32 v[84:85], v[62:63], v[62:63]
	v_pk_mul_f32 v[90:91], v[54:55], v[54:55]
	v_pk_add_f32 v[76:77], v[92:93], v[76:77]
	v_mov_b32_e32 v74, v87
	v_pk_add_f32 v[74:75], v[74:75], v[76:77]
	v_mov_b32_e32 v76, v90
	v_mov_b32_e32 v77, v84
	v_pk_mul_f32 v[78:79], v[64:65], v[64:65]
	v_pk_mul_f32 v[88:89], v[56:57], v[56:57]
	v_pk_add_f32 v[74:75], v[76:77], v[74:75]
	v_mov_b32_e32 v84, v91
	v_pk_add_f32 v[74:75], v[84:85], v[74:75]
	v_mov_b32_e32 v76, v88
	v_mov_b32_e32 v77, v78
	v_pk_add_f32 v[74:75], v[76:77], v[74:75]
	v_mov_b32_e32 v78, v89
	v_pk_add_f32 v[74:75], v[78:79], v[74:75]
	v_xor_b32_e32 v96, 4, v200
	v_cmp_lt_i32_e32 vcc, v96, v95
	v_bfe_u32 v94, v111, 3, 1
	v_ashrrev_i32_e32 v117, 31, v116
	v_cndmask_b32_e32 v78, v200, v96, vcc
	v_lshlrev_b32_e32 v92, 2, v78
	v_lshl_or_b32 v78, s3, 4, v94
	s_waitcnt lgkmcnt(0)
	v_add_f32_dpp v76, v74, v74 quad_perm:[1,0,3,2] row_mask:0xf bank_mask:0xf
	v_add_f32_dpp v77, v75, v75 quad_perm:[1,0,3,2] row_mask:0xf bank_mask:0xf
	v_or_b32_e32 v84, s9, v78
	v_readlane_b32 s8, v255, 40
	v_readlane_b32 s9, v255, 41
	v_mov_b32_e32 v75, v1
	v_mov_b32_e32 v74, s8
	s_movk_i32 s3, 0x900
	s_waitcnt lgkmcnt(0)
	v_add_f32_dpp v78, v76, v76 quad_perm:[2,3,0,1] row_mask:0xf bank_mask:0xf
	v_add_f32_dpp v79, v77, v77 quad_perm:[2,3,0,1] row_mask:0xf bank_mask:0xf
	v_mad_i64_i32 v[74:75], s[8:9], v84, s3, v[74:75]
	v_lshlrev_b32_e32 v76, 1, v83
	v_mov_b32_e32 v77, v1
	v_lshl_add_u64 v[76:77], s[6:7], 0, v[76:77]
	s_mov_b32 s6, 0x358637bd
	s_waitcnt lgkmcnt(0)
	v_add_f32_dpp v84, v78, v78 row_half_mirror row_mask:0xf bank_mask:0xf
	v_add_f32_dpp v85, v79, v79 row_half_mirror row_mask:0xf bank_mask:0xf
	v_mov_b64_e32 v[78:79], s[6:7]
	s_mov_b32 s6, 0x3c800000
	v_pk_fma_f32 v[84:85], v[84:85], s[6:7], v[78:79] op_sel_hi:[1,0,0]
	v_lshl_add_u64 v[86:87], v[74:75], 0, v[116:117]
	v_mul_f32_e32 v83, 0x4b800000, v85
	v_cmp_gt_f32_e32 vcc, s33, v85
	v_lshlrev_b64 v[86:87], 7, v[86:87]
	v_lshl_add_u64 v[86:87], v[76:77], 0, v[86:87]
	v_cndmask_b32_e32 v83, v85, v83, vcc
	v_rsq_f32_e32 v83, v83
	v_readlane_b32 s13, v253, 13
	v_readlane_b32 s14, v253, 14
	v_readlane_b32 s15, v253, 15
	v_mul_f32_e32 v85, 0x45800000, v83
	v_cndmask_b32_e32 v83, v83, v85, vcc
	v_mul_f32_e32 v88, v80, v83
	s_waitcnt vmcnt(0)
	v_pk_mul_f32 v[90:91], v[70:71], v[88:89] op_sel_hi:[1,0]
	v_cmp_gt_f32_e32 vcc, s33, v84
	v_pk_mul_f32 v[58:59], v[58:59], v[90:91]
	v_pk_mul_f32 v[90:91], v[72:73], v[88:89] op_sel_hi:[1,0]
	v_cvt_pk_bf16_f32 v58, v58, v59
	v_pk_mul_f32 v[60:61], v[60:61], v[90:91]
	v_pk_mul_f32 v[90:91], v[66:67], v[88:89] op_sel_hi:[1,0]
	v_cvt_pk_bf16_f32 v59, v60, v61
	v_mul_f32_e32 v60, 0x4b800000, v84
	v_cndmask_b32_e32 v60, v84, v60, vcc
	v_rsq_f32_e32 v83, v60
	v_pk_mul_f32 v[88:89], v[68:69], v[88:89] op_sel_hi:[1,0]
	v_pk_mul_f32 v[62:63], v[62:63], v[90:91]
	v_pk_mul_f32 v[64:65], v[64:65], v[88:89]
	v_cvt_pk_bf16_f32 v60, v62, v63
	v_cvt_pk_bf16_f32 v61, v64, v65
	global_store_dwordx4 v[86:87], v[58:61], off
	v_pk_mul_f32 v[86:87], v[34:35], v[34:35]
	v_pk_mul_f32 v[84:85], v[36:37], v[36:37]
	v_mul_f32_e32 v58, 0x45800000, v83
	v_cndmask_b32_e32 v58, v83, v58, vcc
	v_mul_f32_e32 v58, v80, v58
	v_pk_mul_f32 v[60:61], v[70:71], v[58:59] op_sel_hi:[1,0]
	v_mov_b32_e32 v88, v86
	v_pk_mul_f32 v[50:51], v[50:51], v[60:61]
	v_pk_mul_f32 v[60:61], v[72:73], v[58:59] op_sel_hi:[1,0]
	v_mov_b32_e32 v90, v84
	v_pk_mul_f32 v[52:53], v[52:53], v[60:61]
	v_pk_mul_f32 v[60:61], v[66:67], v[58:59] op_sel_hi:[1,0]
	v_pk_mul_f32 v[58:59], v[68:69], v[58:59] op_sel_hi:[1,0]
	v_pk_mul_f32 v[54:55], v[54:55], v[60:61]
	v_pk_mul_f32 v[60:61], v[42:43], v[42:43]
	v_pk_mul_f32 v[56:57], v[56:57], v[58:59]
	v_pk_mul_f32 v[58:59], v[44:45], v[44:45]
	v_mov_b32_e32 v89, v60
	v_mov_b32_e32 v60, v87
	v_pk_add_f32 v[60:61], v[88:89], v[60:61]
	v_mov_b32_e32 v91, v58
	v_pk_mul_f32 v[64:65], v[46:47], v[46:47]
	v_pk_mul_f32 v[88:89], v[38:39], v[38:39]
	v_pk_add_f32 v[60:61], v[90:91], v[60:61]
	v_mov_b32_e32 v58, v85
	v_pk_add_f32 v[58:59], v[58:59], v[60:61]
	v_mov_b32_e32 v60, v88
	v_mov_b32_e32 v61, v64
	v_pk_mul_f32 v[62:63], v[48:49], v[48:49]
	v_pk_mul_f32 v[86:87], v[40:41], v[40:41]
	v_pk_add_f32 v[58:59], v[60:61], v[58:59]
	v_mov_b32_e32 v64, v89
	v_pk_add_f32 v[58:59], v[64:65], v[58:59]
	v_mov_b32_e32 v60, v86
	v_mov_b32_e32 v61, v62
	v_pk_add_f32 v[58:59], v[60:61], v[58:59]
	v_mov_b32_e32 v62, v87
	v_pk_add_f32 v[58:59], v[62:63], v[58:59]
	v_cvt_pk_bf16_f32 v50, v50, v51
	v_cvt_pk_bf16_f32 v51, v52, v53
	v_cvt_pk_bf16_f32 v52, v54, v55
	v_add_u32_e32 v62, 16, v116
	s_waitcnt lgkmcnt(0)
	v_add_f32_dpp v54, v58, v58 quad_perm:[1,0,3,2] row_mask:0xf bank_mask:0xf
	v_add_f32_dpp v55, v59, v59 quad_perm:[1,0,3,2] row_mask:0xf bank_mask:0xf
	v_ashrrev_i32_e32 v63, 31, v62
	v_cvt_pk_bf16_f32 v53, v56, v57
	v_lshl_add_u64 v[56:57], v[74:75], 0, v[62:63]
	v_lshlrev_b64 v[56:57], 7, v[56:57]
	s_waitcnt lgkmcnt(0)
	v_add_f32_dpp v54, v54, v54 quad_perm:[2,3,0,1] row_mask:0xf bank_mask:0xf
	v_add_f32_dpp v55, v55, v55 quad_perm:[2,3,0,1] row_mask:0xf bank_mask:0xf
	v_lshl_add_u64 v[56:57], v[76:77], 0, v[56:57]
	global_store_dwordx4 v[56:57], v[50:53], off
	v_readlane_b32 s16, v253, 16
	v_readlane_b32 s17, v253, 17
	s_waitcnt lgkmcnt(0)
	v_add_f32_dpp v52, v54, v54 row_half_mirror row_mask:0xf bank_mask:0xf
	v_add_f32_dpp v53, v55, v55 row_half_mirror row_mask:0xf bank_mask:0xf
	v_add_u32_e32 v50, 32, v116
	v_pk_fma_f32 v[52:53], v[52:53], s[6:7], v[78:79] op_sel_hi:[1,0,0]
	v_ashrrev_i32_e32 v51, 31, v50
	v_mul_f32_e32 v54, 0x4b800000, v53
	v_cmp_gt_f32_e32 vcc, s33, v53
	v_lshl_add_u64 v[50:51], v[74:75], 0, v[50:51]
	v_lshlrev_b64 v[50:51], 7, v[50:51]
	v_cndmask_b32_e32 v53, v53, v54, vcc
	v_rsq_f32_e32 v53, v53
	v_lshl_add_u64 v[50:51], v[76:77], 0, v[50:51]
	v_readlane_b32 s22, v253, 22
	v_readlane_b32 s23, v253, 23
	v_mul_f32_e32 v54, 0x45800000, v53
	v_cndmask_b32_e32 v53, v53, v54, vcc
	v_mul_f32_e32 v54, v80, v53
	v_pk_mul_f32 v[56:57], v[70:71], v[54:55] op_sel_hi:[1,0]
	v_cmp_gt_f32_e32 vcc, s33, v52
	v_pk_mul_f32 v[42:43], v[42:43], v[56:57]
	v_pk_mul_f32 v[56:57], v[72:73], v[54:55] op_sel_hi:[1,0]
	v_cvt_pk_bf16_f32 v42, v42, v43
	v_pk_mul_f32 v[44:45], v[44:45], v[56:57]
	v_pk_mul_f32 v[56:57], v[66:67], v[54:55] op_sel_hi:[1,0]
	v_cvt_pk_bf16_f32 v43, v44, v45
	v_mul_f32_e32 v44, 0x4b800000, v52
	v_cndmask_b32_e32 v44, v52, v44, vcc
	v_rsq_f32_e32 v52, v44
	v_pk_mul_f32 v[54:55], v[68:69], v[54:55] op_sel_hi:[1,0]
	v_pk_mul_f32 v[46:47], v[46:47], v[56:57]
	v_pk_mul_f32 v[48:49], v[48:49], v[54:55]
	v_cvt_pk_bf16_f32 v44, v46, v47
	v_cvt_pk_bf16_f32 v45, v48, v49
	global_store_dwordx4 v[50:51], v[42:45], off
	v_pk_mul_f32 v[50:51], v[20:21], v[20:21]
	v_pk_mul_f32 v[48:49], v[30:31], v[30:31]
	v_mul_f32_e32 v42, 0x45800000, v52
	v_cndmask_b32_e32 v42, v52, v42, vcc
	v_mul_f32_e32 v42, v80, v42
	v_pk_mul_f32 v[44:45], v[70:71], v[42:43] op_sel_hi:[1,0]
	v_pk_mul_f32 v[52:53], v[18:19], v[18:19]
	v_pk_mul_f32 v[34:35], v[34:35], v[44:45]
	v_pk_mul_f32 v[44:45], v[72:73], v[42:43] op_sel_hi:[1,0]
	v_mov_b32_e32 v54, v52
	v_pk_mul_f32 v[36:37], v[36:37], v[44:45]
	v_pk_mul_f32 v[44:45], v[66:67], v[42:43] op_sel_hi:[1,0]
	v_pk_mul_f32 v[42:43], v[68:69], v[42:43] op_sel_hi:[1,0]
	v_pk_mul_f32 v[38:39], v[38:39], v[44:45]
	v_pk_mul_f32 v[44:45], v[26:27], v[26:27]
	v_pk_mul_f32 v[40:41], v[40:41], v[42:43]
	v_pk_mul_f32 v[42:43], v[28:29], v[28:29]
	v_mov_b32_e32 v55, v44
	v_mov_b32_e32 v44, v53
	v_pk_add_f32 v[44:45], v[54:55], v[44:45]
	v_mov_b32_e32 v56, v50
	v_mov_b32_e32 v57, v42
	v_pk_mul_f32 v[54:55], v[22:23], v[22:23]
	v_pk_add_f32 v[44:45], v[56:57], v[44:45]
	v_mov_b32_e32 v42, v51
	v_pk_add_f32 v[42:43], v[42:43], v[44:45]
	v_mov_b32_e32 v44, v54
	v_mov_b32_e32 v45, v48
	v_pk_mul_f32 v[46:47], v[32:33], v[32:33]
	v_pk_mul_f32 v[52:53], v[24:25], v[24:25]
	v_pk_add_f32 v[42:43], v[44:45], v[42:43]
	v_mov_b32_e32 v48, v55
	v_pk_add_f32 v[42:43], v[48:49], v[42:43]
	v_mov_b32_e32 v44, v52
	v_mov_b32_e32 v45, v46
	v_pk_add_f32 v[42:43], v[44:45], v[42:43]
	v_mov_b32_e32 v46, v53
	v_pk_add_f32 v[42:43], v[46:47], v[42:43]
	v_cvt_pk_bf16_f32 v34, v34, v35
	v_cvt_pk_bf16_f32 v35, v36, v37
	v_cvt_pk_bf16_f32 v36, v38, v39
	v_add_u32_e32 v46, 48, v116
	s_waitcnt lgkmcnt(0)
	v_add_f32_dpp v38, v42, v42 quad_perm:[1,0,3,2] row_mask:0xf bank_mask:0xf
	v_add_f32_dpp v39, v43, v43 quad_perm:[1,0,3,2] row_mask:0xf bank_mask:0xf
	v_ashrrev_i32_e32 v47, 31, v46
	v_cvt_pk_bf16_f32 v37, v40, v41
	v_lshl_add_u64 v[40:41], v[74:75], 0, v[46:47]
	v_lshlrev_b64 v[40:41], 7, v[40:41]
	s_waitcnt lgkmcnt(0)
	v_add_f32_dpp v38, v38, v38 quad_perm:[2,3,0,1] row_mask:0xf bank_mask:0xf
	v_add_f32_dpp v39, v39, v39 quad_perm:[2,3,0,1] row_mask:0xf bank_mask:0xf
	v_lshl_add_u64 v[40:41], v[76:77], 0, v[40:41]
	global_store_dwordx4 v[40:41], v[34:37], off
	v_readlane_b32 s24, v253, 24
	v_readlane_b32 s25, v253, 25
	s_waitcnt lgkmcnt(0)
	v_add_f32_dpp v36, v38, v38 row_half_mirror row_mask:0xf bank_mask:0xf
	v_add_f32_dpp v37, v39, v39 row_half_mirror row_mask:0xf bank_mask:0xf
	v_add_u32_e32 v34, 64, v116
	v_pk_fma_f32 v[36:37], v[36:37], s[6:7], v[78:79] op_sel_hi:[1,0,0]
	v_ashrrev_i32_e32 v35, 31, v34
	v_mul_f32_e32 v38, 0x4b800000, v37
	v_cmp_gt_f32_e32 vcc, s33, v37
	v_lshl_add_u64 v[34:35], v[74:75], 0, v[34:35]
	v_lshlrev_b64 v[34:35], 7, v[34:35]
	v_cndmask_b32_e32 v37, v37, v38, vcc
	v_rsq_f32_e32 v37, v37
	v_lshl_add_u64 v[34:35], v[76:77], 0, v[34:35]
	v_readlane_b32 s26, v253, 26
	v_readlane_b32 s27, v253, 27
	v_mul_f32_e32 v38, 0x45800000, v37
	v_cndmask_b32_e32 v37, v37, v38, vcc
	v_mul_f32_e32 v38, v80, v37
	v_pk_mul_f32 v[40:41], v[70:71], v[38:39] op_sel_hi:[1,0]
	v_cmp_gt_f32_e32 vcc, s33, v36
	v_pk_mul_f32 v[26:27], v[26:27], v[40:41]
	v_pk_mul_f32 v[40:41], v[72:73], v[38:39] op_sel_hi:[1,0]
	v_cvt_pk_bf16_f32 v26, v26, v27
	v_pk_mul_f32 v[28:29], v[28:29], v[40:41]
	v_pk_mul_f32 v[40:41], v[66:67], v[38:39] op_sel_hi:[1,0]
	v_cvt_pk_bf16_f32 v27, v28, v29
	v_mul_f32_e32 v28, 0x4b800000, v36
	v_cndmask_b32_e32 v28, v36, v28, vcc
	v_rsq_f32_e32 v36, v28
	v_pk_mul_f32 v[38:39], v[68:69], v[38:39] op_sel_hi:[1,0]
	v_pk_mul_f32 v[30:31], v[30:31], v[40:41]
	v_pk_mul_f32 v[32:33], v[32:33], v[38:39]
	v_cvt_pk_bf16_f32 v28, v30, v31
	v_cvt_pk_bf16_f32 v29, v32, v33
	global_store_dwordx4 v[34:35], v[26:29], off
	v_pk_mul_f32 v[34:35], v[4:5], v[4:5]
	v_pk_mul_f32 v[32:33], v[14:15], v[14:15]
	v_mul_f32_e32 v26, 0x45800000, v36
	v_cndmask_b32_e32 v26, v36, v26, vcc
	v_mul_f32_e32 v26, v80, v26
	v_pk_mul_f32 v[28:29], v[70:71], v[26:27] op_sel_hi:[1,0]
	v_pk_mul_f32 v[36:37], v[2:3], v[2:3]
	v_pk_mul_f32 v[18:19], v[18:19], v[28:29]
	v_pk_mul_f32 v[28:29], v[72:73], v[26:27] op_sel_hi:[1,0]
	v_mov_b32_e32 v38, v36
	v_pk_mul_f32 v[20:21], v[20:21], v[28:29]
	v_pk_mul_f32 v[28:29], v[66:67], v[26:27] op_sel_hi:[1,0]
	v_pk_mul_f32 v[26:27], v[68:69], v[26:27] op_sel_hi:[1,0]
	v_pk_mul_f32 v[22:23], v[22:23], v[28:29]
	v_pk_mul_f32 v[28:29], v[10:11], v[10:11]
	v_pk_mul_f32 v[24:25], v[24:25], v[26:27]
	v_pk_mul_f32 v[26:27], v[12:13], v[12:13]
	v_mov_b32_e32 v39, v28
	v_mov_b32_e32 v28, v37
	v_pk_add_f32 v[28:29], v[38:39], v[28:29]
	v_mov_b32_e32 v40, v34
	v_mov_b32_e32 v41, v26
	v_pk_mul_f32 v[38:39], v[6:7], v[6:7]
	v_pk_add_f32 v[28:29], v[40:41], v[28:29]
	v_mov_b32_e32 v26, v35
	v_pk_add_f32 v[26:27], v[26:27], v[28:29]
	v_mov_b32_e32 v28, v38
	v_mov_b32_e32 v29, v32
	v_pk_mul_f32 v[30:31], v[16:17], v[16:17]
	v_pk_mul_f32 v[36:37], v[8:9], v[8:9]
	v_pk_add_f32 v[26:27], v[28:29], v[26:27]
	v_mov_b32_e32 v32, v39
	v_pk_add_f32 v[26:27], v[32:33], v[26:27]
	v_mov_b32_e32 v28, v36
	v_mov_b32_e32 v29, v30
	v_pk_add_f32 v[26:27], v[28:29], v[26:27]
	v_mov_b32_e32 v30, v37
	v_pk_add_f32 v[26:27], v[30:31], v[26:27]
	v_cvt_pk_bf16_f32 v18, v18, v19
	v_cvt_pk_bf16_f32 v19, v20, v21
	v_cvt_pk_bf16_f32 v20, v22, v23
	v_add_u32_e32 v30, 0x50, v116
	s_waitcnt lgkmcnt(0)
	v_add_f32_dpp v22, v26, v26 quad_perm:[1,0,3,2] row_mask:0xf bank_mask:0xf
	v_add_f32_dpp v23, v27, v27 quad_perm:[1,0,3,2] row_mask:0xf bank_mask:0xf
	v_ashrrev_i32_e32 v31, 31, v30
	v_cvt_pk_bf16_f32 v21, v24, v25
	v_lshl_add_u64 v[24:25], v[74:75], 0, v[30:31]
	v_lshlrev_b64 v[24:25], 7, v[24:25]
	s_waitcnt lgkmcnt(0)
	v_add_f32_dpp v22, v22, v22 quad_perm:[2,3,0,1] row_mask:0xf bank_mask:0xf
	v_add_f32_dpp v23, v23, v23 quad_perm:[2,3,0,1] row_mask:0xf bank_mask:0xf
	v_lshl_add_u64 v[24:25], v[76:77], 0, v[24:25]
	global_store_dwordx4 v[24:25], v[18:21], off
	s_waitcnt lgkmcnt(0)
	s_nop 0
	v_add_f32_dpp v20, v22, v22 row_half_mirror row_mask:0xf bank_mask:0xf
	v_add_f32_dpp v21, v23, v23 row_half_mirror row_mask:0xf bank_mask:0xf
	v_add_u32_e32 v18, 0x60, v116
	v_pk_fma_f32 v[20:21], v[20:21], s[6:7], v[78:79] op_sel_hi:[1,0,0]
	v_ashrrev_i32_e32 v19, 31, v18
	v_mul_f32_e32 v22, 0x4b800000, v21
	v_cmp_gt_f32_e32 vcc, s33, v21
	v_lshl_add_u64 v[18:19], v[74:75], 0, v[18:19]
	v_lshlrev_b64 v[18:19], 7, v[18:19]
	v_cndmask_b32_e32 v21, v21, v22, vcc
	v_rsq_f32_e32 v21, v21
	v_lshl_add_u64 v[18:19], v[76:77], 0, v[18:19]
	v_mul_f32_e32 v22, 0x45800000, v21
	v_cndmask_b32_e32 v21, v21, v22, vcc
	v_mul_f32_e32 v22, v80, v21
	v_pk_mul_f32 v[24:25], v[70:71], v[22:23] op_sel_hi:[1,0]
	v_cmp_gt_f32_e32 vcc, s33, v20
	v_pk_mul_f32 v[10:11], v[10:11], v[24:25]
	v_pk_mul_f32 v[24:25], v[72:73], v[22:23] op_sel_hi:[1,0]
	v_cvt_pk_bf16_f32 v10, v10, v11
	v_pk_mul_f32 v[12:13], v[12:13], v[24:25]
	v_pk_mul_f32 v[24:25], v[66:67], v[22:23] op_sel_hi:[1,0]
	v_cvt_pk_bf16_f32 v11, v12, v13
	v_mul_f32_e32 v12, 0x4b800000, v20
	v_cndmask_b32_e32 v12, v20, v12, vcc
	v_rsq_f32_e32 v20, v12
	v_pk_mul_f32 v[22:23], v[68:69], v[22:23] op_sel_hi:[1,0]
	v_pk_mul_f32 v[14:15], v[14:15], v[24:25]
	v_pk_mul_f32 v[16:17], v[16:17], v[22:23]
	v_cvt_pk_bf16_f32 v12, v14, v15
	v_cvt_pk_bf16_f32 v13, v16, v17
	global_store_dwordx4 v[18:19], v[10:13], off
	s_nop 1
	v_mul_f32_e32 v10, 0x45800000, v20
	v_cndmask_b32_e32 v10, v20, v10, vcc
	v_mul_f32_e32 v10, v80, v10
	v_pk_mul_f32 v[12:13], v[70:71], v[10:11] op_sel_hi:[1,0]
	s_nop 0
	v_pk_mul_f32 v[2:3], v[2:3], v[12:13]
	v_pk_mul_f32 v[12:13], v[72:73], v[10:11] op_sel_hi:[1,0]
	v_cvt_pk_bf16_f32 v2, v2, v3
	v_pk_mul_f32 v[4:5], v[4:5], v[12:13]
	v_pk_mul_f32 v[12:13], v[66:67], v[10:11] op_sel_hi:[1,0]
	v_pk_mul_f32 v[10:11], v[68:69], v[10:11] op_sel_hi:[1,0]
	v_pk_mul_f32 v[6:7], v[6:7], v[12:13]
	v_pk_mul_f32 v[8:9], v[8:9], v[10:11]
	v_add_u32_e32 v10, 0x70, v116
	v_ashrrev_i32_e32 v11, 31, v10
	v_cvt_pk_bf16_f32 v3, v4, v5
	v_cvt_pk_bf16_f32 v4, v6, v7
	v_lshl_add_u64 v[6:7], v[74:75], 0, v[10:11]
	v_lshlrev_b64 v[6:7], 7, v[6:7]
	v_cvt_pk_bf16_f32 v5, v8, v9
	v_lshl_add_u64 v[6:7], v[76:77], 0, v[6:7]
	global_store_dwordx4 v[6:7], v[2:5], off
	s_branch .LBB0_240
